# residual epilogue x loads with sc0 (L1 bypass)
# baseline (speedup 1.0000x reference)
;     __device__ __forceinline__ void fused(f32x4 (&acc)[2][2][4][2], const Unit& u, int wr, int wc, int fr, int fq, ldsp lds, int wid, int lane) const {
;         const int rowt = u.pm * BM, b = rowt >> 11;
;         const char* xsb = (const char*)(xs + (size_t)rowt * D + u.pn * BM);
;         char* xdb = (char*)(xd + (size_t)rowt * D + u.pn * BM);
;         const char* gp = (const char*)(gate + (size_t)b * NMOD + u.pn * BM);
;         const unsigned coff = (unsigned)(wc * 32 + 4 * fq) * 4u;
;         unsigned off0 = (unsigned)(wr * 64 + fr) * (D * 4u) + coff; asm volatile("" : "+v"(off0));
; #pragma unroll
;         for (int bj = 0; bj < 2; ++bj)
; #pragma unroll
;             for (int n = 0; n < 2; ++n) { const f32x4 gv = *(const f32x4*)(gp + coff + (bj * HALF + n * 16) * 4);
; #pragma unroll
;                 for (int ai = 0; ai < 2; ++ai) {
; #pragma unroll
;                     for (int m = 0; m < 4; ++m) { const unsigned off = off0 + (unsigned)((ai * HALF + m * 16) * D + bj * HALF + n * 16) * 4u;
;                         const f32x4 xv = *(const f32x4*)(xsb + off); acc[ai][bj][m][n] = xv + gv * acc[ai][bj][m][n];
;                         if (!fin) *(f32x4*)(xdb + off) = acc[ai][bj][m][n]; }
;                     asm volatile("" ::: "memory"); } }
.LBB0_352:
	v_readlane_b32 s8, v255, 19
	s_lshl_b32 s5, s8, 2
	v_readlane_b32 s8, v254, 30
	s_add_u32 s5, s8, s5
	v_readlane_b32 s8, v254, 31
	v_readlane_b32 s9, v255, 20
	s_addc_u32 s24, s8, 0
	s_lshl_b32 s8, s3, 8
	s_ashr_i32 s9, s8, 31
	s_ashr_i32 s25, s3, 3
	s_lshl_b64 s[10:11], s[8:9], 12
	v_readlane_b32 s12, v254, 32
	v_readlane_b32 s13, v254, 33
	s_add_u32 s9, s12, s10
	s_addc_u32 s12, s13, s11
	s_lshl_b32 s14, s40, 8
	s_ashr_i32 s15, s14, 31
	s_lshl_b64 s[22:23], s[14:15], 2
	s_add_u32 s42, s9, s22
	s_addc_u32 s43, s12, s23
	s_add_u32 s9, s54, s10
	s_addc_u32 s10, s55, s11
	s_add_u32 s12, s9, s22
	s_addc_u32 s13, s10, s23
	s_mul_hi_i32 s11, s25, 0x1800
	s_mul_i32 s10, s25, 0x1800
	s_lshl_b64 s[30:31], s[10:11], 2
	v_lshl_or_b32 v149, s4, 5, v161
	s_add_u32 s5, s5, s30
	v_lshlrev_b32_e32 v146, 2, v149
	s_addc_u32 s9, s24, s31
	v_lshl_or_b32 v96, v148, 12, v146
	s_add_u32 s22, s5, s22
	s_addc_u32 s23, s9, s23
	v_add_u32_e32 v147, 0x10000, v96
	v_add_u32_e32 v194, 0x20000, v96
	v_add_u32_e32 v195, 0x30000, v96
	v_add_u32_e32 v197, 0x80000, v96
	v_add_u32_e32 v198, 0x90000, v96
	v_add_u32_e32 v199, 0xa0000, v96
	v_add_u32_e32 v200, 0xb0000, v96
	global_load_dwordx4 v[142:145], v146, s[22:23]
	global_load_dwordx4 v[150:153], v146, s[22:23] offset:64
	global_load_dwordx4 v[190:193], v146, s[22:23] offset:512
	global_load_dwordx4 v[162:165], v96, s[42:43] sc0
	global_load_dwordx4 v[166:169], v147, s[42:43] sc0
	global_load_dwordx4 v[170:173], v194, s[42:43] sc0
	global_load_dwordx4 v[174:177], v195, s[42:43] sc0
	global_load_dwordx4 v[178:181], v197, s[42:43] sc0
	global_load_dwordx4 v[182:185], v198, s[42:43] sc0
	global_load_dwordx4 v[226:229], v199, s[42:43] sc0
	global_load_dwordx4 v[230:233], v200, s[42:43] sc0
	global_load_dwordx4 v[234:237], v96, s[42:43] offset:64 sc0
	global_load_dwordx4 v[238:241], v147, s[42:43] offset:64 sc0
	global_load_dwordx4 v[242:245], v194, s[42:43] offset:64 sc0
	global_load_dwordx4 v[246:249], v195, s[42:43] offset:64 sc0
	global_load_dwordx4 v[250:253], v197, s[42:43] offset:64 sc0
	global_load_dwordx4 v[202:205], v198, s[42:43] offset:64 sc0
	global_load_dwordx4 v[206:209], v199, s[42:43] offset:64 sc0
	global_load_dwordx4 v[210:213], v200, s[42:43] offset:64 sc0
	s_waitcnt vmcnt(19)
	s_barrier
	v_cndmask_b32_e64 v134, 0, 1, s[84:85]
	v_cmp_ne_u32_e64 s[10:11], 1, v134
	v_readlane_b32 s36, v255, 14
	v_readlane_b32 s44, v255, 0
	s_mov_b32 s64, 0x41000000
	v_readlane_b32 s65, v254, 51
	v_readlane_b32 s37, v255, 15
	v_readlane_b32 s45, v255, 1
	s_andn2_b64 vcc, exec, s[84:85]
	s_cbranch_vccnz .Lrn_ladder_fin
	s_waitcnt vmcnt(15)
	v_pk_fma_f32 v[140:141], v[128:129], v[144:145], v[164:165]
	v_pk_fma_f32 v[138:139], v[126:127], v[142:143], v[162:163]
	global_store_dwordx4 v96, v[138:141], s[12:13] nt
	global_load_dwordx4 v[162:165], v96, s[42:43] offset:512 sc0
	s_waitcnt vmcnt(16)
	v_pk_fma_f32 v[136:137], v[124:125], v[144:145], v[168:169]
	v_pk_fma_f32 v[134:135], v[122:123], v[142:143], v[166:167]
	global_store_dwordx4 v147, v[134:137], s[12:13] nt
	global_load_dwordx4 v[166:169], v147, s[42:43] offset:512 sc0
	s_waitcnt vmcnt(17)
	v_pk_fma_f32 v[132:133], v[116:117], v[144:145], v[172:173]
	v_pk_fma_f32 v[130:131], v[114:115], v[142:143], v[170:171]
	global_store_dwordx4 v194, v[130:133], s[12:13] nt
	global_load_dwordx4 v[170:173], v194, s[42:43] offset:512 sc0
	s_waitcnt vmcnt(18)
	v_pk_fma_f32 v[128:129], v[108:109], v[144:145], v[176:177]
	v_pk_fma_f32 v[126:127], v[106:107], v[142:143], v[174:175]
	global_store_dwordx4 v195, v[126:129], s[12:13] nt
	global_load_dwordx4 v[174:177], v195, s[42:43] offset:512 sc0
	s_waitcnt vmcnt(19)
	v_pk_fma_f32 v[124:125], v[100:101], v[144:145], v[180:181]
	v_pk_fma_f32 v[122:123], v[98:99], v[142:143], v[178:179]
	global_store_dwordx4 v197, v[122:125], s[12:13] nt
	global_load_dwordx4 v[178:181], v197, s[42:43] offset:512 sc0
	s_waitcnt vmcnt(20)
	v_pk_fma_f32 v[116:117], v[90:91], v[144:145], v[184:185]
	v_pk_fma_f32 v[114:115], v[88:89], v[142:143], v[182:183]
	global_store_dwordx4 v198, v[114:117], s[12:13] nt
	global_load_dwordx4 v[182:185], v198, s[42:43] offset:512 sc0
	s_waitcnt vmcnt(21)
	v_pk_fma_f32 v[108:109], v[82:83], v[144:145], v[228:229]
	v_pk_fma_f32 v[106:107], v[80:81], v[142:143], v[226:227]
	global_store_dwordx4 v199, v[106:109], s[12:13] nt
	global_load_dwordx4 v[226:229], v199, s[42:43] offset:512 sc0
	s_waitcnt vmcnt(22)
	v_pk_fma_f32 v[100:101], v[74:75], v[144:145], v[232:233]
	v_pk_fma_f32 v[98:99], v[72:73], v[142:143], v[230:231]
	global_store_dwordx4 v200, v[98:101], s[12:13] nt
	global_load_dwordx4 v[230:233], v200, s[42:43] offset:512 sc0
	global_load_dwordx4 v[142:145], v146, s[22:23] offset:576
	s_waitcnt vmcnt(24)
	v_pk_fma_f32 v[94:95], v[94:95], v[152:153], v[236:237]
	v_pk_fma_f32 v[92:93], v[92:93], v[150:151], v[234:235]
	global_store_dwordx4 v96, v[92:95], s[12:13] offset:64 nt
	global_load_dwordx4 v[234:237], v96, s[42:43] offset:576 sc0
	s_waitcnt vmcnt(25)
	v_pk_fma_f32 v[90:91], v[86:87], v[152:153], v[240:241]
	v_pk_fma_f32 v[88:89], v[84:85], v[150:151], v[238:239]
	global_store_dwordx4 v147, v[88:91], s[12:13] offset:64 nt
	global_load_dwordx4 v[238:241], v147, s[42:43] offset:576 sc0
	s_waitcnt vmcnt(26)
	v_pk_fma_f32 v[86:87], v[78:79], v[152:153], v[244:245]
	v_pk_fma_f32 v[84:85], v[76:77], v[150:151], v[242:243]
	global_store_dwordx4 v194, v[84:87], s[12:13] offset:64 nt
	global_load_dwordx4 v[242:245], v194, s[42:43] offset:576 sc0
	s_waitcnt vmcnt(27)
	v_pk_fma_f32 v[82:83], v[70:71], v[152:153], v[248:249]
	v_pk_fma_f32 v[80:81], v[68:69], v[150:151], v[246:247]
	global_store_dwordx4 v195, v[80:83], s[12:13] offset:64 nt
	global_load_dwordx4 v[246:249], v195, s[42:43] offset:576 sc0
	s_waitcnt vmcnt(28)
;     __device__ __forceinline__ void fused(f32x4 (&acc)[2][2][4][2], const Unit& u, int wr, int wc, int fr, int fq, ldsp lds, int wid, int lane) const {
;     ...
; #pragma unroll
;         for (int bj = 0; bj < 2; ++bj)
; #pragma unroll
;             for (int n = 0; n < 2; ++n) { const f32x4 gv = *(const f32x4*)(gp + coff + (bj * HALF + n * 16) * 4);
; #pragma unroll
;                 for (int ai = 0; ai < 2; ++ai) {
; #pragma unroll
;                     for (int m = 0; m < 4; ++m) { const unsigned off = off0 + (unsigned)((ai * HALF + m * 16) * D + bj * HALF + n * 16) * 4u;
;                         const f32x4 xv = *(const f32x4*)(xsb + off); acc[ai][bj][m][n] = xv + gv * acc[ai][bj][m][n];
;                         if (!fin) *(f32x4*)(xdb + off) = acc[ai][bj][m][n]; }
;                     asm volatile("" ::: "memory"); } }
	v_pk_fma_f32 v[78:79], v[66:67], v[152:153], v[252:253]
	v_pk_fma_f32 v[76:77], v[64:65], v[150:151], v[250:251]
	global_store_dwordx4 v197, v[76:79], s[12:13] offset:64 nt
	global_load_dwordx4 v[250:253], v197, s[42:43] offset:576 sc0
	s_waitcnt vmcnt(29)
	v_pk_fma_f32 v[74:75], v[62:63], v[152:153], v[204:205]
	v_pk_fma_f32 v[72:73], v[60:61], v[150:151], v[202:203]
	global_store_dwordx4 v198, v[72:75], s[12:13] offset:64 nt
	global_load_dwordx4 v[202:205], v198, s[42:43] offset:576 sc0
	s_waitcnt vmcnt(30)
	v_pk_fma_f32 v[70:71], v[54:55], v[152:153], v[208:209]
	v_pk_fma_f32 v[68:69], v[52:53], v[150:151], v[206:207]
	global_store_dwordx4 v199, v[68:71], s[12:13] offset:64 nt
	global_load_dwordx4 v[206:209], v199, s[42:43] offset:576 sc0
	s_waitcnt vmcnt(31)
	v_pk_fma_f32 v[66:67], v[46:47], v[152:153], v[212:213]
	v_pk_fma_f32 v[64:65], v[44:45], v[150:151], v[210:211]
	global_store_dwordx4 v200, v[64:67], s[12:13] offset:64 nt
	global_load_dwordx4 v[210:213], v200, s[42:43] offset:576 sc0
	s_waitcnt vmcnt(31)
	v_pk_fma_f32 v[62:63], v[58:59], v[192:193], v[164:165]
	v_pk_fma_f32 v[60:61], v[56:57], v[190:191], v[162:163]
	global_store_dwordx4 v96, v[60:63], s[12:13] offset:512 nt
	s_waitcnt vmcnt(30)
	v_pk_fma_f32 v[58:59], v[50:51], v[192:193], v[168:169]
	v_pk_fma_f32 v[56:57], v[48:49], v[190:191], v[166:167]
	global_store_dwordx4 v147, v[56:59], s[12:13] offset:512 nt
	s_waitcnt vmcnt(29)
	v_pk_fma_f32 v[54:55], v[42:43], v[192:193], v[172:173]
	v_pk_fma_f32 v[52:53], v[40:41], v[190:191], v[170:171]
	global_store_dwordx4 v194, v[52:55], s[12:13] offset:512 nt
	s_waitcnt vmcnt(28)
	v_pk_fma_f32 v[50:51], v[38:39], v[192:193], v[176:177]
	v_pk_fma_f32 v[48:49], v[36:37], v[190:191], v[174:175]
	global_store_dwordx4 v195, v[48:51], s[12:13] offset:512 nt
	s_waitcnt vmcnt(27)
	v_pk_fma_f32 v[46:47], v[34:35], v[192:193], v[180:181]
	v_pk_fma_f32 v[44:45], v[32:33], v[190:191], v[178:179]
	global_store_dwordx4 v197, v[44:47], s[12:13] offset:512 nt
	s_waitcnt vmcnt(26)
	v_pk_fma_f32 v[42:43], v[30:31], v[192:193], v[184:185]
	v_pk_fma_f32 v[40:41], v[28:29], v[190:191], v[182:183]
	global_store_dwordx4 v198, v[40:43], s[12:13] offset:512 nt
	s_waitcnt vmcnt(25)
	v_pk_fma_f32 v[38:39], v[26:27], v[192:193], v[228:229]
	v_pk_fma_f32 v[36:37], v[24:25], v[190:191], v[226:227]
	global_store_dwordx4 v199, v[36:39], s[12:13] offset:512 nt
	s_waitcnt vmcnt(24)
	v_pk_fma_f32 v[34:35], v[22:23], v[192:193], v[232:233]
	v_pk_fma_f32 v[32:33], v[20:21], v[190:191], v[230:231]
	global_store_dwordx4 v200, v[32:35], s[12:13] offset:512 nt
	s_waitcnt vmcnt(22)
	v_pk_fma_f32 v[30:31], v[120:121], v[144:145], v[236:237]
	v_pk_fma_f32 v[28:29], v[118:119], v[142:143], v[234:235]
	global_store_dwordx4 v96, v[28:31], s[12:13] offset:576 nt
	s_waitcnt vmcnt(21)
	v_pk_fma_f32 v[26:27], v[112:113], v[144:145], v[240:241]
	v_pk_fma_f32 v[24:25], v[110:111], v[142:143], v[238:239]
	global_store_dwordx4 v147, v[24:27], s[12:13] offset:576 nt
	s_waitcnt vmcnt(20)
	v_pk_fma_f32 v[22:23], v[104:105], v[144:145], v[244:245]
	v_pk_fma_f32 v[20:21], v[102:103], v[142:143], v[242:243]
	global_store_dwordx4 v194, v[20:23], s[12:13] offset:576 nt
	s_waitcnt vmcnt(19)
	v_pk_fma_f32 v[18:19], v[18:19], v[144:145], v[248:249]
	v_pk_fma_f32 v[16:17], v[16:17], v[142:143], v[246:247]
	global_store_dwordx4 v195, v[16:19], s[12:13] offset:576 nt
	s_waitcnt vmcnt(18)
	v_pk_fma_f32 v[14:15], v[14:15], v[144:145], v[252:253]
	v_pk_fma_f32 v[12:13], v[12:13], v[142:143], v[250:251]
	global_store_dwordx4 v197, v[12:15], s[12:13] offset:576 nt
	s_waitcnt vmcnt(17)
	v_pk_fma_f32 v[10:11], v[10:11], v[144:145], v[204:205]
	v_pk_fma_f32 v[8:9], v[8:9], v[142:143], v[202:203]
	global_store_dwordx4 v198, v[8:11], s[12:13] offset:576 nt
	s_waitcnt vmcnt(16)
	v_pk_fma_f32 v[6:7], v[6:7], v[144:145], v[208:209]
	v_pk_fma_f32 v[4:5], v[4:5], v[142:143], v[206:207]
	global_store_dwordx4 v199, v[4:7], s[12:13] offset:576 nt
	s_waitcnt vmcnt(15)
	v_pk_fma_f32 v[2:3], v[2:3], v[144:145], v[212:213]
	v_pk_fma_f32 v[0:1], v[0:1], v[142:143], v[210:211]
	global_store_dwordx4 v200, v[0:3], s[12:13] offset:576 nt
	s_branch .Lrn_ladder_done
;     __device__ __forceinline__ void fused(f32x4 (&acc)[2][2][4][2], const Unit& u, int wr, int wc, int fr, int fq, ldsp lds, int wid, int lane) const {
;     ...
; #pragma unroll
;         for (int bj = 0; bj < 2; ++bj)
; #pragma unroll
;             for (int n = 0; n < 2; ++n) { const f32x4 gv = *(const f32x4*)(gp + coff + (bj * HALF + n * 16) * 4);
; #pragma unroll
;                 for (int ai = 0; ai < 2; ++ai) {
; #pragma unroll
;                     for (int m = 0; m < 4; ++m) { const unsigned off = off0 + (unsigned)((ai * HALF + m * 16) * D + bj * HALF + n * 16) * 4u;
;                         const f32x4 xv = *(const f32x4*)(xsb + off); acc[ai][bj][m][n] = xv + gv * acc[ai][bj][m][n];
;                         if (!fin) *(f32x4*)(xdb + off) = acc[ai][bj][m][n]; }
;                     asm volatile("" ::: "memory"); } }
.Lrn_ladder_fin:
	s_waitcnt vmcnt(15)
	v_pk_fma_f32 v[140:141], v[128:129], v[144:145], v[164:165]
	v_pk_fma_f32 v[138:139], v[126:127], v[142:143], v[162:163]
	global_load_dwordx4 v[162:165], v96, s[42:43] offset:512 sc0
	s_waitcnt vmcnt(15)
	v_pk_fma_f32 v[136:137], v[124:125], v[144:145], v[168:169]
	v_pk_fma_f32 v[134:135], v[122:123], v[142:143], v[166:167]
	global_load_dwordx4 v[166:169], v147, s[42:43] offset:512 sc0
	s_waitcnt vmcnt(15)
	v_pk_fma_f32 v[132:133], v[116:117], v[144:145], v[172:173]
	v_pk_fma_f32 v[130:131], v[114:115], v[142:143], v[170:171]
	global_load_dwordx4 v[170:173], v194, s[42:43] offset:512 sc0
	s_waitcnt vmcnt(15)
	v_pk_fma_f32 v[128:129], v[108:109], v[144:145], v[176:177]
	v_pk_fma_f32 v[126:127], v[106:107], v[142:143], v[174:175]
	global_load_dwordx4 v[174:177], v195, s[42:43] offset:512 sc0
	s_waitcnt vmcnt(15)
	v_pk_fma_f32 v[124:125], v[100:101], v[144:145], v[180:181]
	v_pk_fma_f32 v[122:123], v[98:99], v[142:143], v[178:179]
	global_load_dwordx4 v[178:181], v197, s[42:43] offset:512 sc0
	s_waitcnt vmcnt(15)
	v_pk_fma_f32 v[116:117], v[90:91], v[144:145], v[184:185]
	v_pk_fma_f32 v[114:115], v[88:89], v[142:143], v[182:183]
	global_load_dwordx4 v[182:185], v198, s[42:43] offset:512 sc0
	s_waitcnt vmcnt(15)
	v_pk_fma_f32 v[108:109], v[82:83], v[144:145], v[228:229]
	v_pk_fma_f32 v[106:107], v[80:81], v[142:143], v[226:227]
	global_load_dwordx4 v[226:229], v199, s[42:43] offset:512 sc0
	s_waitcnt vmcnt(15)
	v_pk_fma_f32 v[100:101], v[74:75], v[144:145], v[232:233]
	v_pk_fma_f32 v[98:99], v[72:73], v[142:143], v[230:231]
	global_load_dwordx4 v[230:233], v200, s[42:43] offset:512 sc0
	global_load_dwordx4 v[142:145], v146, s[22:23] offset:576
	s_waitcnt vmcnt(16)
	v_pk_fma_f32 v[94:95], v[94:95], v[152:153], v[236:237]
	v_pk_fma_f32 v[92:93], v[92:93], v[150:151], v[234:235]
	global_load_dwordx4 v[234:237], v96, s[42:43] offset:576 sc0
	s_waitcnt vmcnt(16)
	v_pk_fma_f32 v[90:91], v[86:87], v[152:153], v[240:241]
	v_pk_fma_f32 v[88:89], v[84:85], v[150:151], v[238:239]
	global_load_dwordx4 v[238:241], v147, s[42:43] offset:576 sc0
	s_waitcnt vmcnt(16)
	v_pk_fma_f32 v[86:87], v[78:79], v[152:153], v[244:245]
	v_pk_fma_f32 v[84:85], v[76:77], v[150:151], v[242:243]
	global_load_dwordx4 v[242:245], v194, s[42:43] offset:576 sc0
	s_waitcnt vmcnt(16)
	v_pk_fma_f32 v[82:83], v[70:71], v[152:153], v[248:249]
	v_pk_fma_f32 v[80:81], v[68:69], v[150:151], v[246:247]
	global_load_dwordx4 v[246:249], v195, s[42:43] offset:576 sc0
	s_waitcnt vmcnt(16)
	v_pk_fma_f32 v[78:79], v[66:67], v[152:153], v[252:253]
	v_pk_fma_f32 v[76:77], v[64:65], v[150:151], v[250:251]
	global_load_dwordx4 v[250:253], v197, s[42:43] offset:576 sc0
	s_waitcnt vmcnt(16)
	v_pk_fma_f32 v[74:75], v[62:63], v[152:153], v[204:205]
	v_pk_fma_f32 v[72:73], v[60:61], v[150:151], v[202:203]
	global_load_dwordx4 v[202:205], v198, s[42:43] offset:576 sc0
	s_waitcnt vmcnt(16)
	v_pk_fma_f32 v[70:71], v[54:55], v[152:153], v[208:209]
	v_pk_fma_f32 v[68:69], v[52:53], v[150:151], v[206:207]
	global_load_dwordx4 v[206:209], v199, s[42:43] offset:576 sc0
	s_waitcnt vmcnt(16)
	v_pk_fma_f32 v[66:67], v[46:47], v[152:153], v[212:213]
	v_pk_fma_f32 v[64:65], v[44:45], v[150:151], v[210:211]
	global_load_dwordx4 v[210:213], v200, s[42:43] offset:576 sc0
	s_waitcnt vmcnt(16)
	v_pk_fma_f32 v[62:63], v[58:59], v[192:193], v[164:165]
	v_pk_fma_f32 v[60:61], v[56:57], v[190:191], v[162:163]
	s_waitcnt vmcnt(15)
	v_pk_fma_f32 v[58:59], v[50:51], v[192:193], v[168:169]
	v_pk_fma_f32 v[56:57], v[48:49], v[190:191], v[166:167]
	s_waitcnt vmcnt(14)
	v_pk_fma_f32 v[54:55], v[42:43], v[192:193], v[172:173]
	v_pk_fma_f32 v[52:53], v[40:41], v[190:191], v[170:171]
	s_waitcnt vmcnt(13)
	v_pk_fma_f32 v[50:51], v[38:39], v[192:193], v[176:177]
	v_pk_fma_f32 v[48:49], v[36:37], v[190:191], v[174:175]
	s_waitcnt vmcnt(12)
	v_pk_fma_f32 v[46:47], v[34:35], v[192:193], v[180:181]
	v_pk_fma_f32 v[44:45], v[32:33], v[190:191], v[178:179]
	s_waitcnt vmcnt(11)
	v_pk_fma_f32 v[42:43], v[30:31], v[192:193], v[184:185]
	v_pk_fma_f32 v[40:41], v[28:29], v[190:191], v[182:183]
	s_waitcnt vmcnt(10)
	v_pk_fma_f32 v[38:39], v[26:27], v[192:193], v[228:229]
	v_pk_fma_f32 v[36:37], v[24:25], v[190:191], v[226:227]
	s_waitcnt vmcnt(9)
	v_pk_fma_f32 v[34:35], v[22:23], v[192:193], v[232:233]
	v_pk_fma_f32 v[32:33], v[20:21], v[190:191], v[230:231]
	s_waitcnt vmcnt(7)
	v_pk_fma_f32 v[30:31], v[120:121], v[144:145], v[236:237]
	v_pk_fma_f32 v[28:29], v[118:119], v[142:143], v[234:235]
	s_waitcnt vmcnt(6)
	v_pk_fma_f32 v[26:27], v[112:113], v[144:145], v[240:241]
	v_pk_fma_f32 v[24:25], v[110:111], v[142:143], v[238:239]
	s_waitcnt vmcnt(5)
	v_pk_fma_f32 v[22:23], v[104:105], v[144:145], v[244:245]
	v_pk_fma_f32 v[20:21], v[102:103], v[142:143], v[242:243]
	s_waitcnt vmcnt(4)
	v_pk_fma_f32 v[18:19], v[18:19], v[144:145], v[248:249]
	v_pk_fma_f32 v[16:17], v[16:17], v[142:143], v[246:247]
	s_waitcnt vmcnt(3)
	v_pk_fma_f32 v[14:15], v[14:15], v[144:145], v[252:253]
	v_pk_fma_f32 v[12:13], v[12:13], v[142:143], v[250:251]
	s_waitcnt vmcnt(2)
	v_pk_fma_f32 v[10:11], v[10:11], v[144:145], v[204:205]
	v_pk_fma_f32 v[8:9], v[8:9], v[142:143], v[202:203]
	s_waitcnt vmcnt(1)
	v_pk_fma_f32 v[6:7], v[6:7], v[144:145], v[208:209]
	v_pk_fma_f32 v[4:5], v[4:5], v[142:143], v[206:207]
	s_waitcnt vmcnt(0)
	v_pk_fma_f32 v[2:3], v[2:3], v[144:145], v[212:213]
	v_pk_fma_f32 v[0:1], v[0:1], v[142:143], v[210:211]
